# combined version, tail pre-step made independent of the grid size (tile loop over gridDim)
# baseline (speedup 1.0000x reference)
.LBB0_576:
	s_andn2_b64 vcc, exec, s[4:5]
	s_cbranch_vccnz .LBB0_635
	v_readlane_b32 s4, v254, 0
	v_readlane_b32 s5, v254, 1
	s_load_dwordx2 s[6:7], s[4:5], 0xc0
	v_mov_b32_e32 v0, v192
	v_readlane_b32 s8, v254, 30
	v_readlane_b32 s9, v254, 31
	v_readfirstlane_b32 s4, v0
	v_mov_b32_e32 v0, v192
	s_andn2_b64 vcc, exec, s[8:9]
	s_cbranch_vccnz .LBB0_610
	s_waitcnt lgkmcnt(0)
	s_mul_i32 s5, s20, 0x300000
	s_add_u32 s100, s6, 0xc01000
	s_addc_u32 s101, s7, 0
	s_add_u32 s100, s100, s5
	s_addc_u32 s101, s101, 0
	v_mov_b32_e32 v11, s2
.Ltailpre_recurrent_out_loop:
	s_add_u32 s8, s6, 0x120b5000
	s_addc_u32 s9, s7, 0
	v_and_b32_e32 v4, 15, v192
	v_bfe_u32 v5, v192, 4, 2
	v_lshrrev_b32_e32 v6, 6, v192
	v_lshl_add_u32 v6, v6, 4, v4
	v_readfirstlane_b32 s5, v11
	s_lshr_b32 s5, s5, 6
	s_mul_i32 s5, s5, 0x300
	v_lshlrev_b32_e32 v8, 4, v5
	v_add_u32_e32 v8, s5, v8
	v_mul_u32_u24_e32 v7, 0xc00, v6
	v_add_u32_e32 v7, v7, v8
	v_readfirstlane_b32 s5, v11
	s_and_b32 s5, s5, 63
	s_lshl_b32 s5, s5, 4
	v_add_u32_e32 v9, s5, v4
	v_mul_u32_u24_e32 v9, 0xc00, v9
	v_add_u32_e32 v9, v9, v8
	global_load_dwordx4 v[12:15], v7, s[8:9]
	global_load_dwordx4 v[16:19], v9, s[100:101]
	global_load_dwordx4 v[20:23], v7, s[8:9] offset:64
	global_load_dwordx4 v[24:27], v9, s[100:101] offset:64
	global_load_dwordx4 v[28:31], v7, s[8:9] offset:128
	global_load_dwordx4 v[32:35], v9, s[100:101] offset:128
	global_load_dwordx4 v[36:39], v7, s[8:9] offset:192
	global_load_dwordx4 v[40:43], v9, s[100:101] offset:192
	global_load_dwordx4 v[44:47], v7, s[8:9] offset:256
	global_load_dwordx4 v[48:51], v9, s[100:101] offset:256
	global_load_dwordx4 v[52:55], v7, s[8:9] offset:320
	global_load_dwordx4 v[56:59], v9, s[100:101] offset:320
	global_load_dwordx4 v[60:63], v7, s[8:9] offset:384
	global_load_dwordx4 v[64:67], v9, s[100:101] offset:384
	global_load_dwordx4 v[68:71], v7, s[8:9] offset:448
	global_load_dwordx4 v[72:75], v9, s[100:101] offset:448
	global_load_dwordx4 v[76:79], v7, s[8:9] offset:512
	global_load_dwordx4 v[80:83], v9, s[100:101] offset:512
	global_load_dwordx4 v[84:87], v7, s[8:9] offset:576
	global_load_dwordx4 v[88:91], v9, s[100:101] offset:576
	global_load_dwordx4 v[92:95], v7, s[8:9] offset:640
	global_load_dwordx4 v[96:99], v9, s[100:101] offset:640
	global_load_dwordx4 v[100:103], v7, s[8:9] offset:704
	global_load_dwordx4 v[104:107], v9, s[100:101] offset:704
	v_readfirstlane_b32 s5, v11
	s_lshr_b32 s5, s5, 6
	s_lshl_b32 s5, s5, 19
	v_lshlrev_b32_e32 v10, 11, v6
	v_add_u32_e32 v10, s5, v10
	v_readfirstlane_b32 s5, v11
	s_and_b32 s5, s5, 63
	s_lshl_b32 s5, s5, 5
	v_add_u32_e32 v10, s5, v10
	v_lshl_add_u32 v10, v5, 3, v10
	s_waitcnt vmcnt(22)
	v_mfma_f32_16x16x32_bf16 v[0:3], v[16:19], v[12:15], 0
	s_waitcnt vmcnt(20)
	v_mfma_f32_16x16x32_bf16 v[0:3], v[24:27], v[20:23], v[0:3]
	s_waitcnt vmcnt(18)
	v_mfma_f32_16x16x32_bf16 v[0:3], v[32:35], v[28:31], v[0:3]
	s_waitcnt vmcnt(16)
	v_mfma_f32_16x16x32_bf16 v[0:3], v[40:43], v[36:39], v[0:3]
	s_waitcnt vmcnt(14)
	v_mfma_f32_16x16x32_bf16 v[0:3], v[48:51], v[44:47], v[0:3]
	s_waitcnt vmcnt(12)
	v_mfma_f32_16x16x32_bf16 v[0:3], v[56:59], v[52:55], v[0:3]
	s_waitcnt vmcnt(10)
	v_mfma_f32_16x16x32_bf16 v[0:3], v[64:67], v[60:63], v[0:3]
	s_waitcnt vmcnt(8)
	v_mfma_f32_16x16x32_bf16 v[0:3], v[72:75], v[68:71], v[0:3]
	s_waitcnt vmcnt(6)
	v_mfma_f32_16x16x32_bf16 v[0:3], v[80:83], v[76:79], v[0:3]
	s_waitcnt vmcnt(4)
	v_mfma_f32_16x16x32_bf16 v[0:3], v[88:91], v[84:87], v[0:3]
	s_waitcnt vmcnt(2)
	v_mfma_f32_16x16x32_bf16 v[0:3], v[96:99], v[92:95], v[0:3]
	s_waitcnt vmcnt(0)
	v_mfma_f32_16x16x32_bf16 v[0:3], v[104:107], v[100:103], v[0:3]
	s_add_u32 s8, s6, 0x151f9000
	s_addc_u32 s9, s7, 0
	s_nop 7
	s_nop 7
	v_cvt_pk_bf16_f32 v4, v0, v1
	v_cvt_pk_bf16_f32 v5, v2, v3
	global_store_dwordx2 v10, v[4:5], s[8:9] sc1
	v_add_u32_e32 v11, s42, v11
	v_cmp_gt_u32_e32 vcc, 0x100, v11
	s_cbranch_vccnz .Ltailpre_recurrent_out_loop
	v_mov_b32_e32 v0, v192
	v_readlane_b32 s8, v253, 32
	v_readlane_b32 s9, v253, 33
	s_mul_i32 s8, s20, 0x180000
	s_mov_b32 s5, s9
	v_writelane_b32 v253, s4, 32
	s_lshl_b64 s[8:9], s[8:9], 1
	s_mov_b32 s78, s20
	v_writelane_b32 v253, s5, 33
	s_waitcnt lgkmcnt(0)
	s_add_u32 s5, s6, s8
	s_addc_u32 s8, s7, s9
	s_add_u32 s24, s5, 0xc01000
	s_addc_u32 s25, s8, 0
	v_readlane_b32 s8, v254, 46
	s_mul_i32 s5, s8, 0xc0000
	s_add_u32 s20, s24, s5
	s_mul_hi_i32 s5, s8, 0xc0000
	v_readlane_b32 s8, v254, 23
	v_readlane_b32 s9, v254, 24
	s_addc_u32 s21, s25, s5
	s_andn2_b64 vcc, exec, s[8:9]
	s_mov_b32 s62, 24
	s_cbranch_vccnz .LBB0_580
	v_readlane_b32 s5, v253, 16
	s_add_u32 s20, s20, s5
	v_readlane_b32 s5, v253, 12
	s_addc_u32 s21, s21, s5
	s_mov_b32 s62, 4

.LBB0_858:
	s_andn2_b64 vcc, exec, s[4:5]
	s_cbranch_vccnz .LBB0_923
	v_readlane_b32 s4, v254, 0
	v_readlane_b32 s5, v254, 1
	s_load_dwordx2 s[10:11], s[4:5], 0xc0
	v_mov_b32_e32 v0, v192
	v_readlane_b32 s4, v254, 21
	v_readlane_b32 s5, v254, 22
	v_readfirstlane_b32 s6, v0
	v_mov_b32_e32 v0, v192
	s_andn2_b64 vcc, exec, s[4:5]
	s_cbranch_vccnz .LBB0_898
	s_waitcnt lgkmcnt(0)
	v_readlane_b32 s7, v253, 36
	s_mul_i32 s7, s7, 0x200000
	s_add_u32 s100, s10, 0x1e01000
	s_addc_u32 s101, s11, 0
	s_add_u32 s100, s100, s7
	s_addc_u32 s101, s101, 0
	v_mov_b32_e32 v11, s2
.Ltailpre_attention_out_loop:
	s_add_u32 s4, s10, 0x110b1000
	s_addc_u32 s5, s11, 0
	v_and_b32_e32 v4, 15, v192
	v_bfe_u32 v5, v192, 4, 2
	v_lshrrev_b32_e32 v6, 6, v192
	v_lshl_add_u32 v6, v6, 4, v4
	v_readfirstlane_b32 s7, v11
	s_lshr_b32 s7, s7, 6
	s_mul_i32 s7, s7, 0x200
	v_lshlrev_b32_e32 v8, 4, v5
	v_add_u32_e32 v8, s7, v8
	v_mul_u32_u24_e32 v7, 0x800, v6
	v_add_u32_e32 v7, v7, v8
	v_readfirstlane_b32 s7, v11
	s_and_b32 s7, s7, 63
	s_lshl_b32 s7, s7, 4
	v_add_u32_e32 v9, s7, v4
	v_mul_u32_u24_e32 v9, 0x800, v9
	v_add_u32_e32 v9, v9, v8
	global_load_dwordx4 v[12:15], v7, s[4:5]
	global_load_dwordx4 v[16:19], v9, s[100:101]
	global_load_dwordx4 v[20:23], v7, s[4:5] offset:64
	global_load_dwordx4 v[24:27], v9, s[100:101] offset:64
	global_load_dwordx4 v[28:31], v7, s[4:5] offset:128
	global_load_dwordx4 v[32:35], v9, s[100:101] offset:128
	global_load_dwordx4 v[36:39], v7, s[4:5] offset:192
	global_load_dwordx4 v[40:43], v9, s[100:101] offset:192
	global_load_dwordx4 v[44:47], v7, s[4:5] offset:256
	global_load_dwordx4 v[48:51], v9, s[100:101] offset:256
	global_load_dwordx4 v[52:55], v7, s[4:5] offset:320
	global_load_dwordx4 v[56:59], v9, s[100:101] offset:320
	global_load_dwordx4 v[60:63], v7, s[4:5] offset:384
	global_load_dwordx4 v[64:67], v9, s[100:101] offset:384
	global_load_dwordx4 v[68:71], v7, s[4:5] offset:448
	global_load_dwordx4 v[72:75], v9, s[100:101] offset:448
	v_readfirstlane_b32 s7, v11
	s_lshr_b32 s7, s7, 6
	s_lshl_b32 s7, s7, 19
	v_lshlrev_b32_e32 v10, 11, v6
	v_add_u32_e32 v10, s7, v10
	v_readfirstlane_b32 s7, v11
	s_and_b32 s7, s7, 63
	s_lshl_b32 s7, s7, 5
	v_add_u32_e32 v10, s7, v10
	v_lshl_add_u32 v10, v5, 3, v10
	s_waitcnt vmcnt(14)
	v_mfma_f32_16x16x32_bf16 v[0:3], v[16:19], v[12:15], 0
	s_waitcnt vmcnt(12)
	v_mfma_f32_16x16x32_bf16 v[0:3], v[24:27], v[20:23], v[0:3]
	s_waitcnt vmcnt(10)
	v_mfma_f32_16x16x32_bf16 v[0:3], v[32:35], v[28:31], v[0:3]
	s_waitcnt vmcnt(8)
	v_mfma_f32_16x16x32_bf16 v[0:3], v[40:43], v[36:39], v[0:3]
	s_waitcnt vmcnt(6)
	v_mfma_f32_16x16x32_bf16 v[0:3], v[48:51], v[44:47], v[0:3]
	s_waitcnt vmcnt(4)
	v_mfma_f32_16x16x32_bf16 v[0:3], v[56:59], v[52:55], v[0:3]
	s_waitcnt vmcnt(2)
	v_mfma_f32_16x16x32_bf16 v[0:3], v[64:67], v[60:63], v[0:3]
	s_waitcnt vmcnt(0)
	v_mfma_f32_16x16x32_bf16 v[0:3], v[72:75], v[68:71], v[0:3]
	s_add_u32 s4, s10, 0x151f9000
	s_addc_u32 s5, s11, 0
	s_nop 7
	s_nop 7
	v_cvt_pk_bf16_f32 v4, v0, v1
	v_cvt_pk_bf16_f32 v5, v2, v3
	global_store_dwordx2 v10, v[4:5], s[4:5] sc1
	v_add_u32_e32 v11, s42, v11
	v_cmp_gt_u32_e32 vcc, 0x100, v11
	s_cbranch_vccnz .Ltailpre_attention_out_loop
	v_mov_b32_e32 v0, v192
	v_readlane_b32 s4, v254, 25
	v_readlane_b32 s5, v254, 26
	s_andn2_b64 vcc, exec, s[4:5]
	v_readlane_b32 s4, v253, 13
	v_readlane_b32 s5, v253, 14
	s_cbranch_vccnz .LBB0_862
	v_readlane_b32 s4, v253, 1
	v_readlane_b32 s5, v253, 2

.LBB0_1040:
	s_andn2_b64 vcc, exec, s[4:5]
	s_cbranch_vccnz .LBB0_1103
	v_readlane_b32 s4, v254, 0
	v_readlane_b32 s5, v254, 1
	s_load_dwordx4 s[8:11], s[4:5], 0xb8
	v_mov_b32_e32 v0, v192
	v_readlane_b32 s6, v254, 36
	v_readlane_b32 s7, v254, 37
	v_readfirstlane_b32 s4, v0
	v_mov_b32_e32 v0, v192
	s_andn2_b64 vcc, exec, s[6:7]
	s_cbranch_vccnz .LBB0_1078
	s_waitcnt lgkmcnt(0)
	s_mul_i32 s5, s20, 0x580000
	s_add_u32 s100, s8, 0x2088000
	s_addc_u32 s101, s9, 0
	s_add_u32 s100, s100, s5
	s_addc_u32 s101, s101, 0
	v_mov_b32_e32 v11, s2
.Ltailpre_FFN_out_loop:
	s_add_u32 s6, s10, 0xe727000
	s_addc_u32 s7, s11, 0
	v_and_b32_e32 v4, 15, v192
	v_bfe_u32 v5, v192, 4, 2
	v_lshrrev_b32_e32 v6, 6, v192
	v_lshl_add_u32 v6, v6, 4, v4
	v_readfirstlane_b32 s5, v11
	s_lshr_b32 s5, s5, 6
	s_mul_i32 s5, s5, 0x580
	v_lshlrev_b32_e32 v8, 4, v5
	v_add_u32_e32 v8, s5, v8
	v_mul_u32_u24_e32 v7, 0x1600, v6
	v_add_u32_e32 v7, v7, v8
	v_readfirstlane_b32 s5, v11
	s_and_b32 s5, s5, 63
	s_lshl_b32 s5, s5, 4
	v_add_u32_e32 v9, s5, v4
	v_mul_u32_u24_e32 v9, 0x1600, v9
	v_add_u32_e32 v9, v9, v8
	global_load_dwordx4 v[12:15], v7, s[6:7]
	global_load_dwordx4 v[16:19], v9, s[100:101]
	global_load_dwordx4 v[20:23], v7, s[6:7] offset:64
	global_load_dwordx4 v[24:27], v9, s[100:101] offset:64
	global_load_dwordx4 v[28:31], v7, s[6:7] offset:128
	global_load_dwordx4 v[32:35], v9, s[100:101] offset:128
	global_load_dwordx4 v[36:39], v7, s[6:7] offset:192
	global_load_dwordx4 v[40:43], v9, s[100:101] offset:192
	global_load_dwordx4 v[44:47], v7, s[6:7] offset:256
	global_load_dwordx4 v[48:51], v9, s[100:101] offset:256
	global_load_dwordx4 v[52:55], v7, s[6:7] offset:320
	global_load_dwordx4 v[56:59], v9, s[100:101] offset:320
	global_load_dwordx4 v[60:63], v7, s[6:7] offset:384
	global_load_dwordx4 v[64:67], v9, s[100:101] offset:384
	global_load_dwordx4 v[68:71], v7, s[6:7] offset:448
	global_load_dwordx4 v[72:75], v9, s[100:101] offset:448
	global_load_dwordx4 v[76:79], v7, s[6:7] offset:512
	global_load_dwordx4 v[80:83], v9, s[100:101] offset:512
	global_load_dwordx4 v[84:87], v7, s[6:7] offset:576
	global_load_dwordx4 v[88:91], v9, s[100:101] offset:576
	global_load_dwordx4 v[92:95], v7, s[6:7] offset:640
	global_load_dwordx4 v[96:99], v9, s[100:101] offset:640
	global_load_dwordx4 v[100:103], v7, s[6:7] offset:704
	global_load_dwordx4 v[104:107], v9, s[100:101] offset:704
	global_load_dwordx4 v[108:111], v7, s[6:7] offset:768
	global_load_dwordx4 v[112:115], v9, s[100:101] offset:768
	global_load_dwordx4 v[116:119], v7, s[6:7] offset:832
	global_load_dwordx4 v[120:123], v9, s[100:101] offset:832
	global_load_dwordx4 v[124:127], v7, s[6:7] offset:896
	global_load_dwordx4 v[128:131], v9, s[100:101] offset:896
	global_load_dwordx4 v[132:135], v7, s[6:7] offset:960
	global_load_dwordx4 v[136:139], v9, s[100:101] offset:960
	global_load_dwordx4 v[140:143], v7, s[6:7] offset:1024
	global_load_dwordx4 v[144:147], v9, s[100:101] offset:1024
	global_load_dwordx4 v[148:151], v7, s[6:7] offset:1088
	global_load_dwordx4 v[152:155], v9, s[100:101] offset:1088
	global_load_dwordx4 v[156:159], v7, s[6:7] offset:1152
	global_load_dwordx4 v[160:163], v9, s[100:101] offset:1152
	global_load_dwordx4 v[164:167], v7, s[6:7] offset:1216
	global_load_dwordx4 v[168:171], v9, s[100:101] offset:1216
	global_load_dwordx4 v[204:207], v7, s[6:7] offset:1280
	global_load_dwordx4 v[208:211], v9, s[100:101] offset:1280
	global_load_dwordx4 v[212:215], v7, s[6:7] offset:1344
	global_load_dwordx4 v[216:219], v9, s[100:101] offset:1344
	v_readfirstlane_b32 s5, v11
	s_lshr_b32 s5, s5, 6
	s_lshl_b32 s5, s5, 19
	v_lshlrev_b32_e32 v10, 11, v6
	v_add_u32_e32 v10, s5, v10
	v_readfirstlane_b32 s5, v11
	s_and_b32 s5, s5, 63
	s_lshl_b32 s5, s5, 5
	v_add_u32_e32 v10, s5, v10
	v_lshl_add_u32 v10, v5, 3, v10
	s_waitcnt vmcnt(42)
	v_mfma_f32_16x16x32_bf16 v[0:3], v[16:19], v[12:15], 0
	s_waitcnt vmcnt(40)
	v_mfma_f32_16x16x32_bf16 v[0:3], v[24:27], v[20:23], v[0:3]
	s_waitcnt vmcnt(38)
	v_mfma_f32_16x16x32_bf16 v[0:3], v[32:35], v[28:31], v[0:3]
	s_waitcnt vmcnt(36)
	v_mfma_f32_16x16x32_bf16 v[0:3], v[40:43], v[36:39], v[0:3]
	s_waitcnt vmcnt(34)
	v_mfma_f32_16x16x32_bf16 v[0:3], v[48:51], v[44:47], v[0:3]
	s_waitcnt vmcnt(32)
	v_mfma_f32_16x16x32_bf16 v[0:3], v[56:59], v[52:55], v[0:3]
	s_waitcnt vmcnt(30)
	v_mfma_f32_16x16x32_bf16 v[0:3], v[64:67], v[60:63], v[0:3]
	s_waitcnt vmcnt(28)
	v_mfma_f32_16x16x32_bf16 v[0:3], v[72:75], v[68:71], v[0:3]
	s_waitcnt vmcnt(26)
	v_mfma_f32_16x16x32_bf16 v[0:3], v[80:83], v[76:79], v[0:3]
	s_waitcnt vmcnt(24)
	v_mfma_f32_16x16x32_bf16 v[0:3], v[88:91], v[84:87], v[0:3]
	s_waitcnt vmcnt(22)
	v_mfma_f32_16x16x32_bf16 v[0:3], v[96:99], v[92:95], v[0:3]
	s_waitcnt vmcnt(20)
	v_mfma_f32_16x16x32_bf16 v[0:3], v[104:107], v[100:103], v[0:3]
	s_waitcnt vmcnt(18)
	v_mfma_f32_16x16x32_bf16 v[0:3], v[112:115], v[108:111], v[0:3]
	s_waitcnt vmcnt(16)
	v_mfma_f32_16x16x32_bf16 v[0:3], v[120:123], v[116:119], v[0:3]
	s_waitcnt vmcnt(14)
	v_mfma_f32_16x16x32_bf16 v[0:3], v[128:131], v[124:127], v[0:3]
	s_waitcnt vmcnt(12)
	v_mfma_f32_16x16x32_bf16 v[0:3], v[136:139], v[132:135], v[0:3]
	s_waitcnt vmcnt(10)
	v_mfma_f32_16x16x32_bf16 v[0:3], v[144:147], v[140:143], v[0:3]
	s_waitcnt vmcnt(8)
	v_mfma_f32_16x16x32_bf16 v[0:3], v[152:155], v[148:151], v[0:3]
	s_waitcnt vmcnt(6)
	v_mfma_f32_16x16x32_bf16 v[0:3], v[160:163], v[156:159], v[0:3]
	s_waitcnt vmcnt(4)
	v_mfma_f32_16x16x32_bf16 v[0:3], v[168:171], v[164:167], v[0:3]
	s_waitcnt vmcnt(2)
	v_mfma_f32_16x16x32_bf16 v[0:3], v[208:211], v[204:207], v[0:3]
	s_waitcnt vmcnt(0)
	v_mfma_f32_16x16x32_bf16 v[0:3], v[216:219], v[212:215], v[0:3]
	s_add_u32 s6, s10, 0x151f9000
	s_addc_u32 s7, s11, 0
	s_nop 7
	s_nop 7
	v_cvt_pk_bf16_f32 v4, v0, v1
	v_cvt_pk_bf16_f32 v5, v2, v3
	global_store_dwordx2 v10, v[4:5], s[6:7] sc1
	v_add_u32_e32 v11, s42, v11
	v_cmp_gt_u32_e32 vcc, 0x100, v11
	s_cbranch_vccnz .Ltailpre_FFN_out_loop
	v_mov_b32_e32 v0, v192
	v_readlane_b32 s6, v253, 32
	v_readlane_b32 s7, v253, 33
	s_mul_i32 s6, s20, 0x2c0000
	s_mov_b32 s5, s7
	v_writelane_b32 v253, s4, 32
	s_lshl_b64 s[6:7], s[6:7], 1
	s_mov_b32 s65, 44
	v_writelane_b32 v253, s5, 33
	s_waitcnt lgkmcnt(0)
	s_add_u32 s5, s8, s6
	s_addc_u32 s6, s9, s7
	s_add_u32 s26, s5, 0x2088000
	s_addc_u32 s27, s6, 0
	v_readlane_b32 s6, v253, 21
	s_mul_i32 s5, s6, 0x160000
	s_add_u32 s20, s26, s5
	s_mul_hi_i32 s5, s6, 0x160000
	v_readlane_b32 s6, v254, 23
	v_readlane_b32 s7, v254, 24
	s_addc_u32 s21, s27, s5
	s_andn2_b64 vcc, exec, s[6:7]
	s_cbranch_vccnz .LBB0_1044
	v_readlane_b32 s5, v253, 26
	s_add_u32 s20, s20, s5
	v_readlane_b32 s5, v253, 24
	s_addc_u32 s21, s21, s5
	s_mov_b32 s65, 4
